# v15 + FFN-up epilogue: removed 64 dead zero-inits before full-row DPP rotates
# speedup vs baseline: 1.0020x; 1.0010x over previous
.LBB0_1169:
	ds_read_b128 v[166:169], v220
	v_mov_b32_dpp v231, v114 row_ror:1 row_mask:0xf bank_mask:0xf
	v_mov_b32_dpp v227, v126 row_ror:15 row_mask:0xf bank_mask:0xf
	v_mov_b32_dpp v232, v115 row_ror:1 row_mask:0xf bank_mask:0xf
	v_mov_b32_dpp v228, v127 row_ror:15 row_mask:0xf bank_mask:0xf
	v_mov_b32_dpp v229, v116 row_ror:1 row_mask:0xf bank_mask:0xf
	v_mov_b32_dpp v225, v128 row_ror:15 row_mask:0xf bank_mask:0xf
	v_mov_b32_dpp v230, v117 row_ror:1 row_mask:0xf bank_mask:0xf
	v_mov_b32_dpp v226, v129 row_ror:15 row_mask:0xf bank_mask:0xf
	ds_read_b128 v[138:141], v218 offset:512
	ds_read_b128 v[142:145], v218 offset:1536
	ds_read_b128 v[134:137], v218 offset:2560
	ds_read_b128 v[130:133], v218 offset:3584
	s_movk_i32 s2, 0x200
	s_and_b64 vcc, exec, s[62:63]
	v_mov_b32_e32 v147, 0
	v_mov_b32_e32 v148, 0
	v_mov_b32_e32 v149, 0
	s_cbranch_vccnz .LBB0_1171
	ds_read_b128 v[146:149], v219 offset:288
	s_movk_i32 s2, 0x400
.LBB0_1171:
	s_waitcnt lgkmcnt(5)
	v_cndmask_b32_e64 v170, v231, v170, s[48:49]
	v_cndmask_b32_e64 v171, v232, v171, s[48:49]
	v_pk_mul_f32 v[170:171], v[150:151], v[170:171]
	v_pk_mul_f32 v[202:203], v[118:119], v[162:163]
	v_pk_fma_f32 v[170:171], v[126:127], v[162:163], v[170:171]
	v_pk_mul_f32 v[198:199], v[122:123], v[162:163]
	v_pk_fma_f32 v[170:171], v[122:123], v[154:155], v[170:171]
	v_pk_fma_f32 v[122:123], v[122:123], v[150:151], v[202:203]
	s_waitcnt lgkmcnt(4)
	v_cndmask_b32_e64 v167, v228, v167, s[44:45]
	v_pk_fma_f32 v[122:123], v[114:115], v[154:155], v[122:123]
	v_pk_mul_f32 v[114:115], v[114:115], v[162:163]
	v_cndmask_b32_e64 v166, v227, v166, s[44:45]
	v_pk_fma_f32 v[114:115], v[118:119], v[150:151], v[114:115]
	v_pk_fma_f32 v[126:127], v[126:127], v[150:151], v[198:199]
	v_pk_fma_f32 v[114:115], v[154:155], v[166:167], v[114:115]
	v_pk_fma_f32 v[126:127], v[118:119], v[154:155], v[126:127]
	v_pk_add_f32 v[118:119], v[158:159], v[114:115]
	v_cndmask_b32_e64 v172, v229, v172, s[48:49]
	v_mul_f32_e32 v114, 0xbfb8aa3b, v118
	v_cndmask_b32_e64 v173, v230, v173, s[48:49]
	v_exp_f32_e32 v114, v114
	v_mul_f32_e32 v115, 0xbfb8aa3b, v119
	v_pk_mul_f32 v[172:173], v[152:153], v[172:173]
	v_exp_f32_e32 v115, v115
	v_pk_fma_f32 v[172:173], v[128:129], v[164:165], v[172:173]
	v_pk_mul_f32 v[204:205], v[120:121], v[164:165]
	v_pk_fma_f32 v[172:173], v[124:125], v[156:157], v[172:173]
	v_pk_mul_f32 v[200:201], v[124:125], v[164:165]
	v_pk_fma_f32 v[124:125], v[124:125], v[152:153], v[204:205]
	v_add_f32_e32 v114, 1.0, v114
	v_pk_fma_f32 v[124:125], v[116:117], v[156:157], v[124:125]
	v_pk_mul_f32 v[116:117], v[116:117], v[164:165]
	v_rcp_f32_e32 v150, v114
	v_add_f32_e32 v151, 1.0, v115
	v_cndmask_b32_e64 v115, v226, v169, s[44:45]
	v_cndmask_b32_e64 v114, v225, v168, s[44:45]
	v_pk_fma_f32 v[116:117], v[120:121], v[152:153], v[116:117]
	v_pk_fma_f32 v[128:129], v[128:129], v[152:153], v[200:201]
	v_pk_fma_f32 v[114:115], v[156:157], v[114:115], v[116:117]
	v_pk_fma_f32 v[128:129], v[120:121], v[156:157], v[128:129]
	v_pk_add_f32 v[120:121], v[160:161], v[114:115]
	v_mul_f32_e32 v114, 0xbfb8aa3b, v120
	v_exp_f32_e32 v114, v114
	v_mul_f32_e32 v115, 0xbfb8aa3b, v121
	v_exp_f32_e32 v115, v115
	v_add_f32_e32 v114, 1.0, v114
	v_rcp_f32_e32 v152, v114
	v_add_f32_e32 v114, 1.0, v115
	v_rcp_f32_e32 v153, v114
	ds_read_b128 v[114:117], v220 offset:32
	v_pk_add_f32 v[170:171], v[158:159], v[170:171]
	v_pk_add_f32 v[172:173], v[160:161], v[172:173]
	v_mov_b32_dpp v154, v98 row_ror:1 row_mask:0xf bank_mask:0xf
	v_mov_b32_dpp v155, v110 row_ror:15 row_mask:0xf bank_mask:0xf
	v_mul_f32_e32 v178, 0xbfb8aa3b, v170
	v_mul_f32_e32 v179, 0xbfb8aa3b, v171
	v_mul_f32_e32 v180, 0xbfb8aa3b, v172
	v_mul_f32_e32 v181, 0xbfb8aa3b, v173
	s_waitcnt lgkmcnt(1)
	v_cndmask_b32_e64 v146, v154, v146, s[48:49]
	s_waitcnt lgkmcnt(0)
	v_cndmask_b32_e64 v154, v155, v114, s[44:45]
	v_exp_f32_e32 v178, v178
	v_exp_f32_e32 v179, v179
	v_exp_f32_e32 v180, v180
	v_exp_f32_e32 v181, v181
	v_mov_b32_dpp v155, v111 row_ror:15 row_mask:0xf bank_mask:0xf
	v_cndmask_b32_e64 v155, v155, v115, s[44:45]
	v_pk_add_f32 v[126:127], v[158:159], v[126:127]
	v_pk_add_f32 v[128:129], v[160:161], v[128:129]
	v_mov_b32_dpp v114, v99 row_ror:1 row_mask:0xf bank_mask:0xf
	v_mov_b32_dpp v115, v112 row_ror:15 row_mask:0xf bank_mask:0xf
	v_mul_f32_e32 v198, 0xbfb8aa3b, v126
	v_mul_f32_e32 v199, 0xbfb8aa3b, v127
	v_mul_f32_e32 v200, 0xbfb8aa3b, v128
	v_mul_f32_e32 v201, 0xbfb8aa3b, v129
	v_cndmask_b32_e64 v147, v114, v147, s[48:49]
	v_cndmask_b32_e64 v116, v115, v116, s[44:45]
	v_add_f32_e32 v178, 1.0, v178
	v_add_f32_e32 v179, 1.0, v179
	v_add_f32_e32 v180, 1.0, v180
	v_add_f32_e32 v181, 1.0, v181
	v_exp_f32_e32 v198, v198
	v_exp_f32_e32 v199, v199
	v_exp_f32_e32 v200, v200
	v_exp_f32_e32 v201, v201
	v_mov_b32_dpp v114, v100 row_ror:1 row_mask:0xf bank_mask:0xf
	v_mov_b32_dpp v115, v101 row_ror:1 row_mask:0xf bank_mask:0xf
	v_rcp_f32_e32 v178, v178
	v_rcp_f32_e32 v179, v179
	v_rcp_f32_e32 v180, v180
	v_rcp_f32_e32 v181, v181
	v_cndmask_b32_e64 v114, v114, v148, s[48:49]
	v_cndmask_b32_e64 v115, v115, v149, s[48:49]
	v_pk_mul_f32 v[114:115], v[140:141], v[114:115]
	v_pk_mul_f32 v[146:147], v[138:139], v[146:147]
	v_pk_fma_f32 v[146:147], v[110:111], v[142:143], v[146:147]
	v_pk_fma_f32 v[114:115], v[112:113], v[144:145], v[114:115]
	v_add_f32_e32 v198, 1.0, v198
	v_add_f32_e32 v199, 1.0, v199
	v_add_f32_e32 v200, 1.0, v200
	v_add_f32_e32 v201, 1.0, v201
	v_pk_add_f32 v[122:123], v[158:159], v[122:123]
	v_mov_b32_dpp v148, v113 row_ror:15 row_mask:0xf bank_mask:0xf
	v_pk_fma_f32 v[114:115], v[108:109], v[136:137], v[114:115]
	v_pk_fma_f32 v[146:147], v[106:107], v[134:135], v[146:147]
	v_rcp_f32_e32 v198, v198
	v_rcp_f32_e32 v199, v199
	v_rcp_f32_e32 v200, v200
	v_mul_f32_e32 v202, 0xbfb8aa3b, v122
	v_mul_f32_e32 v203, 0xbfb8aa3b, v123
	v_rcp_f32_e32 v201, v201
	v_pk_add_f32 v[124:125], v[160:161], v[124:125]
	v_cndmask_b32_e64 v117, v148, v117, s[44:45]
	v_pk_add_f32 v[146:147], v[130:131], v[146:147]
	v_pk_add_f32 v[114:115], v[132:133], v[114:115]
	v_pk_mul_f32 v[148:149], v[170:171], v[178:179]
	v_pk_mul_f32 v[156:157], v[172:173], v[180:181]
	v_exp_f32_e32 v202, v202
	v_exp_f32_e32 v203, v203
	v_mul_f32_e32 v204, 0xbfb8aa3b, v124
	v_mul_f32_e32 v205, 0xbfb8aa3b, v125
	v_pk_mul_f32 v[156:157], v[156:157], v[114:115]
	v_pk_mul_f32 v[114:115], v[148:149], v[146:147]
	v_pk_mul_f32 v[146:147], v[108:109], v[144:145]
	v_pk_mul_f32 v[148:149], v[106:107], v[142:143]
	v_exp_f32_e32 v204, v204
	v_exp_f32_e32 v205, v205
	v_pk_fma_f32 v[112:113], v[112:113], v[140:141], v[146:147]
	v_pk_fma_f32 v[110:111], v[110:111], v[138:139], v[148:149]
	v_pk_fma_f32 v[112:113], v[104:105], v[136:137], v[112:113]
	v_pk_fma_f32 v[110:111], v[102:103], v[134:135], v[110:111]
	v_pk_add_f32 v[112:113], v[132:133], v[112:113]
	v_pk_add_f32 v[110:111], v[130:131], v[110:111]
	v_pk_mul_f32 v[126:127], v[126:127], v[198:199]
	v_pk_mul_f32 v[128:129], v[128:129], v[200:201]
	v_add_f32_e32 v202, 1.0, v202
	v_add_f32_e32 v203, 1.0, v203
	v_pk_mul_f32 v[112:113], v[128:129], v[112:113]
	v_pk_mul_f32 v[110:111], v[126:127], v[110:111]
	v_pk_mul_f32 v[126:127], v[102:103], v[142:143]
	v_rcp_f32_e32 v202, v202
	v_rcp_f32_e32 v203, v203
	v_add_f32_e32 v204, 1.0, v204
	v_add_f32_e32 v205, 1.0, v205
	v_rcp_f32_e32 v151, v151
	v_cvt_pk_bf16_f32 v114, v114, v115
	v_cvt_pk_bf16_f32 v115, v156, v157
	v_cvt_pk_bf16_f32 v110, v110, v111
	v_cvt_pk_bf16_f32 v111, v112, v113
	v_pk_mul_f32 v[112:113], v[104:105], v[144:145]
	v_pk_fma_f32 v[106:107], v[106:107], v[138:139], v[126:127]
	v_rcp_f32_e32 v204, v204
	v_rcp_f32_e32 v205, v205
	v_pk_fma_f32 v[108:109], v[108:109], v[140:141], v[112:113]
	v_pk_fma_f32 v[106:107], v[98:99], v[134:135], v[106:107]
	v_pk_mul_f32 v[98:99], v[98:99], v[142:143]
	v_pk_fma_f32 v[108:109], v[100:101], v[136:137], v[108:109]
	v_pk_mul_f32 v[100:101], v[100:101], v[144:145]
	v_pk_fma_f32 v[98:99], v[102:103], v[138:139], v[98:99]
	v_pk_fma_f32 v[100:101], v[104:105], v[140:141], v[100:101]
	v_pk_fma_f32 v[98:99], v[134:135], v[154:155], v[98:99]
	v_pk_add_f32 v[106:107], v[130:131], v[106:107]
	v_pk_mul_f32 v[112:113], v[122:123], v[202:203]
	v_pk_fma_f32 v[100:101], v[136:137], v[116:117], v[100:101]
	v_pk_add_f32 v[98:99], v[130:131], v[98:99]
	v_pk_mul_f32 v[102:103], v[118:119], v[150:151]
	v_pk_add_f32 v[108:109], v[132:133], v[108:109]
	v_pk_mul_f32 v[122:123], v[124:125], v[204:205]
	v_pk_mul_f32 v[106:107], v[112:113], v[106:107]
	v_pk_add_f32 v[100:101], v[132:133], v[100:101]
	v_pk_mul_f32 v[104:105], v[120:121], v[152:153]
	v_pk_mul_f32 v[98:99], v[102:103], v[98:99]
	v_pk_mul_f32 v[108:109], v[122:123], v[108:109]
	v_cvt_pk_bf16_f32 v106, v106, v107
	v_pk_mul_f32 v[100:101], v[104:105], v[100:101]
	v_cvt_pk_bf16_f32 v107, v108, v109
	v_cvt_pk_bf16_f32 v98, v98, v99
	v_mov_b32_e32 v128, 0
	v_cvt_pk_bf16_f32 v99, v100, v101
	ds_read_b128 v[132:135], v218
	ds_read_b128 v[144:147], v218 offset:1024
	ds_read_b128 v[136:139], v218 offset:2048
	ds_read_b128 v[140:143], v218 offset:3072
	ds_read_b128 v[156:159], v221 offset:256
	v_cndmask_b32_e64 v100, 0, 1, s[10:11]
	v_cmp_ne_u32_e64 s[60:61], 1, v100
	s_andn2_b64 vcc, exec, s[10:11]
	v_add_u32_e32 v104, s2, v222
	v_mov_b32_e32 v152, 0
	v_mov_b32_e32 v153, 0
	v_mov_b32_e32 v154, 0
	v_mov_b32_e32 v155, 0
	s_cbranch_vccnz .LBB0_1173
	ds_read_b128 v[152:155], v104
.LBB0_1173:
	v_mov_b32_dpp v161, v80 row_ror:1 row_mask:0xf bank_mask:0xf
	v_mov_b32_dpp v109, v92 row_ror:15 row_mask:0xf bank_mask:0xf
	v_mov_b32_dpp v162, v81 row_ror:1 row_mask:0xf bank_mask:0xf
	v_mov_b32_dpp v112, v93 row_ror:15 row_mask:0xf bank_mask:0xf
	v_mov_b32_dpp v113, v82 row_ror:1 row_mask:0xf bank_mask:0xf
	v_mov_b32_dpp v105, v94 row_ror:15 row_mask:0xf bank_mask:0xf
	v_mov_b32_dpp v160, v83 row_ror:1 row_mask:0xf bank_mask:0xf
	v_mov_b32_dpp v108, v95 row_ror:15 row_mask:0xf bank_mask:0xf
	ds_read_b128 v[120:123], v218 offset:512
	ds_read_b128 v[124:127], v218 offset:1536
	ds_read_b128 v[116:119], v218 offset:2560
	ds_read_b128 v[100:103], v218 offset:3584
	ds_read_b128 v[148:151], v221 offset:288
	s_and_b64 vcc, exec, s[60:61]
	v_mov_b32_e32 v129, 0
	v_mov_b32_e32 v130, 0
	v_mov_b32_e32 v131, 0
	s_cbranch_vccnz .LBB0_1175
	ds_read_b128 v[128:131], v104 offset:32
.LBB0_1175:
	s_waitcnt lgkmcnt(5)
	v_cndmask_b32_e64 v159, v160, v159, s[48:49]
	v_cndmask_b32_e64 v158, v113, v158, s[48:49]
	v_pk_mul_f32 v[158:159], v[134:135], v[158:159]
	v_cndmask_b32_e64 v157, v162, v157, s[48:49]
	v_pk_fma_f32 v[158:159], v[94:95], v[146:147], v[158:159]
	v_cndmask_b32_e64 v156, v161, v156, s[48:49]
	v_pk_fma_f32 v[158:159], v[90:91], v[138:139], v[158:159]
	v_pk_mul_f32 v[156:157], v[132:133], v[156:157]
	v_pk_add_f32 v[158:159], v[142:143], v[158:159]
	v_pk_fma_f32 v[156:157], v[92:93], v[144:145], v[156:157]
	v_mul_f32_e32 v113, 0xbfb8aa3b, v158
	v_pk_fma_f32 v[156:157], v[88:89], v[136:137], v[156:157]
	v_exp_f32_e32 v113, v113
	v_mul_f32_e32 v160, 0xbfb8aa3b, v159
	v_pk_add_f32 v[156:157], v[140:141], v[156:157]
	v_exp_f32_e32 v164, v160
	v_mul_f32_e32 v161, 0xbfb8aa3b, v156
	v_exp_f32_e32 v161, v161
	v_mul_f32_e32 v162, 0xbfb8aa3b, v157
	v_exp_f32_e32 v163, v162
	v_add_f32_e32 v113, 1.0, v113
	v_rcp_f32_e32 v160, v113
	v_add_f32_e32 v113, 1.0, v164
	v_pk_mul_f32 v[164:165], v[88:89], v[144:145]
	v_add_f32_e32 v161, 1.0, v161
	v_pk_fma_f32 v[92:93], v[92:93], v[132:133], v[164:165]
	v_rcp_f32_e32 v162, v161
	v_pk_fma_f32 v[92:93], v[84:85], v[136:137], v[92:93]
	v_add_f32_e32 v161, 1.0, v163
	v_pk_add_f32 v[92:93], v[140:141], v[92:93]
	v_rcp_f32_e32 v163, v161
	v_mul_f32_e32 v161, 0xbfb8aa3b, v92
	v_exp_f32_e32 v164, v161
	v_mul_f32_e32 v161, 0xbfb8aa3b, v93
	v_exp_f32_e32 v165, v161
	v_pk_mul_f32 v[166:167], v[90:91], v[146:147]
	v_pk_mul_f32 v[168:169], v[84:85], v[144:145]
	v_pk_fma_f32 v[94:95], v[94:95], v[134:135], v[166:167]
	v_rcp_f32_e32 v161, v113
	v_pk_fma_f32 v[94:95], v[86:87], v[138:139], v[94:95]
	v_add_f32_e32 v113, 1.0, v164
	v_pk_add_f32 v[94:95], v[142:143], v[94:95]
	v_pk_fma_f32 v[88:89], v[88:89], v[132:133], v[168:169]
	v_rcp_f32_e32 v164, v113
	v_add_f32_e32 v113, 1.0, v165
	v_mul_f32_e32 v165, 0xbfb8aa3b, v94
	v_pk_fma_f32 v[88:89], v[80:81], v[136:137], v[88:89]
	v_pk_mul_f32 v[80:81], v[80:81], v[144:145]
	v_exp_f32_e32 v166, v165
	v_mul_f32_e32 v165, 0xbfb8aa3b, v95
	v_cndmask_b32_e64 v152, v109, v152, s[44:45]
	v_cndmask_b32_e64 v153, v112, v153, s[44:45]
	v_pk_fma_f32 v[80:81], v[84:85], v[132:133], v[80:81]
	v_exp_f32_e32 v167, v165
	v_pk_fma_f32 v[80:81], v[136:137], v[152:153], v[80:81]
	v_rcp_f32_e32 v165, v113
	v_pk_add_f32 v[84:85], v[140:141], v[80:81]
	v_add_f32_e32 v113, 1.0, v166
	v_mul_f32_e32 v80, 0xbfb8aa3b, v84
	v_pk_add_f32 v[88:89], v[140:141], v[88:89]
	v_exp_f32_e32 v80, v80
	v_mul_f32_e32 v81, 0xbfb8aa3b, v85
	v_rcp_f32_e32 v166, v113
	v_add_f32_e32 v113, 1.0, v167
	v_mul_f32_e32 v167, 0xbfb8aa3b, v88
	v_exp_f32_e32 v81, v81
	v_exp_f32_e32 v168, v167
	v_mul_f32_e32 v167, 0xbfb8aa3b, v89
	v_pk_mul_f32 v[170:171], v[86:87], v[146:147]
	v_exp_f32_e32 v169, v167
	v_pk_fma_f32 v[90:91], v[90:91], v[134:135], v[170:171]
	v_add_f32_e32 v80, 1.0, v80
	v_pk_fma_f32 v[90:91], v[82:83], v[138:139], v[90:91]
	v_pk_mul_f32 v[82:83], v[82:83], v[146:147]
	v_rcp_f32_e32 v112, v80
	v_add_f32_e32 v109, 1.0, v81
	v_cndmask_b32_e64 v80, v105, v154, s[44:45]
	v_cndmask_b32_e64 v81, v108, v155, s[44:45]
	v_pk_fma_f32 v[82:83], v[86:87], v[134:135], v[82:83]
	v_rcp_f32_e32 v167, v113
	v_add_f32_e32 v113, 1.0, v168
	v_pk_add_f32 v[90:91], v[142:143], v[90:91]
	v_pk_fma_f32 v[80:81], v[138:139], v[80:81], v[82:83]
	v_rcp_f32_e32 v168, v113
	v_add_f32_e32 v113, 1.0, v169
	v_mul_f32_e32 v169, 0xbfb8aa3b, v90
	v_pk_add_f32 v[82:83], v[142:143], v[80:81]
	v_exp_f32_e32 v170, v169
	v_mul_f32_e32 v169, 0xbfb8aa3b, v91
	v_mul_f32_e32 v80, 0xbfb8aa3b, v82
	v_exp_f32_e32 v171, v169
	v_exp_f32_e32 v80, v80
	v_mul_f32_e32 v81, 0xbfb8aa3b, v83
	v_exp_f32_e32 v81, v81
	v_rcp_f32_e32 v169, v113
	v_add_f32_e32 v113, 1.0, v170
	v_rcp_f32_e32 v170, v113
	v_add_f32_e32 v113, 1.0, v171
	v_add_f32_e32 v80, 1.0, v80
	v_mov_b32_dpp v105, v77 row_ror:15 row_mask:0xf bank_mask:0xf
	v_rcp_f32_e32 v171, v113
	v_rcp_f32_e32 v113, v109
	v_rcp_f32_e32 v86, v80
	v_add_f32_e32 v80, 1.0, v81
	s_waitcnt lgkmcnt(0)
	v_cndmask_b32_e64 v109, v105, v129, s[44:45]
	v_mov_b32_dpp v81, v76 row_ror:15 row_mask:0xf bank_mask:0xf
	v_rcp_f32_e32 v87, v80
	v_mov_b32_dpp v105, v66 row_ror:1 row_mask:0xf bank_mask:0xf
	v_cndmask_b32_e64 v108, v81, v128, s[44:45]
	v_cndmask_b32_e64 v128, v105, v150, s[48:49]
	v_mov_b32_dpp v80, v64 row_ror:1 row_mask:0xf bank_mask:0xf
	v_mov_b32_dpp v81, v65 row_ror:1 row_mask:0xf bank_mask:0xf
	v_mov_b32_dpp v129, v78 row_ror:15 row_mask:0xf bank_mask:0xf
	v_mov_b32_dpp v105, v67 row_ror:1 row_mask:0xf bank_mask:0xf
	v_cndmask_b32_e64 v80, v80, v148, s[48:49]
	v_cndmask_b32_e64 v81, v81, v149, s[48:49]
	v_cndmask_b32_e64 v130, v129, v130, s[44:45]
	v_cndmask_b32_e64 v129, v105, v151, s[48:49]
	v_pk_mul_f32 v[128:129], v[122:123], v[128:129]
	v_pk_mul_f32 v[80:81], v[120:121], v[80:81]
	v_pk_fma_f32 v[80:81], v[76:77], v[124:125], v[80:81]
	v_pk_fma_f32 v[128:129], v[78:79], v[126:127], v[128:129]
	v_mov_b32_dpp v132, v79 row_ror:15 row_mask:0xf bank_mask:0xf
	v_pk_fma_f32 v[128:129], v[74:75], v[118:119], v[128:129]
	v_pk_fma_f32 v[80:81], v[72:73], v[116:117], v[80:81]
	v_cndmask_b32_e64 v131, v132, v131, s[44:45]
	v_pk_add_f32 v[80:81], v[100:101], v[80:81]
	v_pk_add_f32 v[128:129], v[102:103], v[128:129]
	v_pk_mul_f32 v[132:133], v[156:157], v[162:163]
	v_pk_mul_f32 v[134:135], v[158:159], v[160:161]
	v_pk_mul_f32 v[80:81], v[132:133], v[80:81]
	v_pk_mul_f32 v[128:129], v[134:135], v[128:129]
	v_cvt_pk_bf16_f32 v80, v80, v81
	v_pk_mul_f32 v[132:133], v[72:73], v[124:125]
	v_cvt_pk_bf16_f32 v81, v128, v129
	v_pk_mul_f32 v[128:129], v[74:75], v[126:127]
	v_pk_fma_f32 v[76:77], v[76:77], v[120:121], v[132:133]
	v_pk_fma_f32 v[78:79], v[78:79], v[122:123], v[128:129]
	v_pk_fma_f32 v[76:77], v[68:69], v[116:117], v[76:77]
	v_pk_fma_f32 v[78:79], v[70:71], v[118:119], v[78:79]
	v_pk_add_f32 v[76:77], v[100:101], v[76:77]
	v_pk_add_f32 v[78:79], v[102:103], v[78:79]
	v_pk_mul_f32 v[92:93], v[92:93], v[164:165]
	v_pk_mul_f32 v[94:95], v[94:95], v[166:167]
	v_pk_mul_f32 v[76:77], v[92:93], v[76:77]
	v_pk_mul_f32 v[78:79], v[94:95], v[78:79]
	v_pk_mul_f32 v[92:93], v[68:69], v[124:125]
	v_cvt_pk_bf16_f32 v76, v76, v77
	v_cvt_pk_bf16_f32 v77, v78, v79
	v_pk_mul_f32 v[78:79], v[70:71], v[126:127]
	v_pk_fma_f32 v[72:73], v[72:73], v[120:121], v[92:93]
	v_pk_fma_f32 v[74:75], v[74:75], v[122:123], v[78:79]
	v_pk_fma_f32 v[72:73], v[64:65], v[116:117], v[72:73]
	v_pk_mul_f32 v[64:65], v[64:65], v[124:125]
	v_pk_fma_f32 v[74:75], v[66:67], v[118:119], v[74:75]
	v_pk_mul_f32 v[66:67], v[66:67], v[126:127]
	v_pk_fma_f32 v[64:65], v[68:69], v[120:121], v[64:65]
	v_pk_fma_f32 v[66:67], v[70:71], v[122:123], v[66:67]
	v_pk_fma_f32 v[64:65], v[116:117], v[108:109], v[64:65]
	v_pk_add_f32 v[72:73], v[100:101], v[72:73]
	v_pk_mul_f32 v[78:79], v[88:89], v[168:169]
	v_pk_fma_f32 v[66:67], v[118:119], v[130:131], v[66:67]
	v_pk_add_f32 v[64:65], v[100:101], v[64:65]
	v_pk_mul_f32 v[68:69], v[84:85], v[112:113]
	v_pk_add_f32 v[74:75], v[102:103], v[74:75]
	v_pk_mul_f32 v[88:89], v[90:91], v[170:171]
	v_pk_mul_f32 v[72:73], v[78:79], v[72:73]
	v_pk_add_f32 v[66:67], v[102:103], v[66:67]
	v_pk_mul_f32 v[70:71], v[82:83], v[86:87]
	v_pk_mul_f32 v[64:65], v[68:69], v[64:65]
	v_pk_mul_f32 v[74:75], v[88:89], v[74:75]
	v_cvt_pk_bf16_f32 v72, v72, v73
	v_pk_mul_f32 v[66:67], v[70:71], v[66:67]
	v_cvt_pk_bf16_f32 v73, v74, v75
	v_cvt_pk_bf16_f32 v64, v64, v65
	v_mov_b32_e32 v134, 0
	v_cvt_pk_bf16_f32 v65, v66, v67
	ds_read_b128 v[100:103], v223 offset:8208
	ds_read_b128 v[126:129], v223 offset:9232
	ds_read_b128 v[118:121], v223 offset:10256
	ds_read_b128 v[122:125], v223 offset:11280
	s_and_b64 vcc, exec, s[62:63]
	v_mov_b32_e32 v138, 0
	v_mov_b32_e32 v139, 0
	v_mov_b32_e32 v140, 0
	v_mov_b32_e32 v141, 0
	s_cbranch_vccnz .LBB0_1177
	ds_read_b128 v[138:141], v219 offset:272
.LBB0_1177:
	ds_read_b128 v[130:133], v220 offset:16
	v_mov_b32_dpp v94, v44 row_ror:1 row_mask:0xf bank_mask:0xf
	v_mov_b32_dpp v74, v56 row_ror:15 row_mask:0xf bank_mask:0xf
	v_mov_b32_dpp v95, v45 row_ror:1 row_mask:0xf bank_mask:0xf
	v_mov_b32_dpp v75, v57 row_ror:15 row_mask:0xf bank_mask:0xf
	v_mov_b32_dpp v78, v46 row_ror:1 row_mask:0xf bank_mask:0xf
	v_mov_b32_dpp v70, v58 row_ror:15 row_mask:0xf bank_mask:0xf
	v_mov_b32_dpp v79, v47 row_ror:1 row_mask:0xf bank_mask:0xf
	v_mov_b32_dpp v71, v59 row_ror:15 row_mask:0xf bank_mask:0xf
	ds_read_b128 v[86:89], v223 offset:8720
	ds_read_b128 v[90:93], v223 offset:9744
	ds_read_b128 v[82:85], v223 offset:10768
	ds_read_b128 v[66:69], v223 offset:11792
	s_and_b64 vcc, exec, s[62:63]
	v_mov_b32_e32 v135, 0
	v_mov_b32_e32 v136, 0
	v_mov_b32_e32 v137, 0
	s_cbranch_vccnz .LBB0_1179
	ds_read_b128 v[134:137], v219 offset:304
.LBB0_1179:
	s_waitcnt lgkmcnt(5)
	v_cndmask_b32_e64 v78, v78, v140, s[48:49]
	v_cndmask_b32_e64 v79, v79, v141, s[48:49]
	v_pk_mul_f32 v[78:79], v[102:103], v[78:79]
	v_cndmask_b32_e64 v94, v94, v138, s[48:49]
	v_pk_fma_f32 v[78:79], v[58:59], v[128:129], v[78:79]
	v_cndmask_b32_e64 v95, v95, v139, s[48:49]
	v_pk_fma_f32 v[78:79], v[54:55], v[120:121], v[78:79]
	v_pk_mul_f32 v[94:95], v[100:101], v[94:95]
	v_pk_add_f32 v[116:117], v[124:125], v[78:79]
	v_pk_fma_f32 v[94:95], v[56:57], v[126:127], v[94:95]
	v_mul_f32_e32 v78, 0xbfb8aa3b, v116
	v_exp_f32_e32 v78, v78
	v_mul_f32_e32 v79, 0xbfb8aa3b, v117
	v_exp_f32_e32 v79, v79
	v_pk_fma_f32 v[94:95], v[52:53], v[118:119], v[94:95]
	v_add_f32_e32 v78, 1.0, v78
	v_pk_add_f32 v[108:109], v[122:123], v[94:95]
	v_rcp_f32_e32 v142, v78
	v_mul_f32_e32 v94, 0xbfb8aa3b, v108
	v_exp_f32_e32 v94, v94
	v_mul_f32_e32 v95, 0xbfb8aa3b, v109
	v_add_f32_e32 v78, 1.0, v79
	v_exp_f32_e32 v95, v95
	v_add_f32_e32 v94, 1.0, v94
	v_mov_b32_dpp v79, v32 row_ror:1 row_mask:0xf bank_mask:0xf
	s_waitcnt lgkmcnt(0)
	v_cndmask_b32_e64 v134, v79, v134, s[48:49]
	v_rcp_f32_e32 v112, v94
	v_mov_b32_dpp v79, v33 row_ror:1 row_mask:0xf bank_mask:0xf
	v_cndmask_b32_e64 v135, v79, v135, s[48:49]
	v_add_f32_e32 v94, 1.0, v95
	v_mov_b32_dpp v105, v35 row_ror:1 row_mask:0xf bank_mask:0xf
	v_mov_b32_dpp v79, v34 row_ror:1 row_mask:0xf bank_mask:0xf
	v_rcp_f32_e32 v113, v94
	v_rcp_f32_e32 v143, v78
	ds_read_b128 v[138:141], v220 offset:48
	v_cndmask_b32_e64 v136, v79, v136, s[48:49]
	v_cndmask_b32_e64 v137, v105, v137, s[48:49]
	v_pk_mul_f32 v[136:137], v[88:89], v[136:137]
	v_pk_mul_f32 v[134:135], v[86:87], v[134:135]
	v_pk_fma_f32 v[136:137], v[42:43], v[92:93], v[136:137]
	v_pk_fma_f32 v[134:135], v[40:41], v[90:91], v[134:135]
	v_pk_fma_f32 v[136:137], v[38:39], v[84:85], v[136:137]
	v_pk_fma_f32 v[134:135], v[36:37], v[82:83], v[134:135]
	s_lshl_b32 s2, s22, 8
	v_mov_b32_dpp v78, v40 row_ror:15 row_mask:0xf bank_mask:0xf
	v_mov_b32_dpp v94, v41 row_ror:15 row_mask:0xf bank_mask:0xf
	v_mov_b32_dpp v95, v42 row_ror:15 row_mask:0xf bank_mask:0xf
	v_mov_b32_dpp v79, v43 row_ror:15 row_mask:0xf bank_mask:0xf
	v_pk_add_f32 v[134:135], v[66:67], v[134:135]
	v_pk_add_f32 v[136:137], v[68:69], v[136:137]
	v_pk_mul_f32 v[108:109], v[108:109], v[112:113]
	v_pk_mul_f32 v[112:113], v[116:117], v[142:143]
	v_pk_mul_f32 v[108:109], v[108:109], v[134:135]
	v_pk_mul_f32 v[112:113], v[112:113], v[136:137]
	v_cvt_pk_bf16_f32 v116, v108, v109
	s_nop 0
	v_cvt_pk_bf16_f32 v117, v112, v113
	s_and_saveexec_b64 s[22:23], s[50:51]
	s_movk_i32 s3, 0x2c00
	s_cbranch_execz .LBB0_1181
	v_add_u32_e32 v105, s2, v194
	v_mov_b64_e32 v[108:109], s[88:89]
	v_mad_i64_i32 v[108:109], s[34:35], v105, s3, v[108:109]
	v_lshl_add_u64 v[108:109], v[188:189], 1, v[108:109]
	global_store_dwordx4 v[108:109], v[114:117], off

.LBB0_1185:
	v_mov_b32_dpp v98, v20 row_ror:1 row_mask:0xf bank_mask:0xf
	v_mov_b32_dpp v78, v24 row_ror:15 row_mask:0xf bank_mask:0xf
	v_mov_b32_dpp v99, v21 row_ror:1 row_mask:0xf bank_mask:0xf
	v_mov_b32_dpp v79, v25 row_ror:15 row_mask:0xf bank_mask:0xf
	v_mov_b32_dpp v82, v22 row_ror:1 row_mask:0xf bank_mask:0xf
	v_mov_b32_dpp v74, v26 row_ror:15 row_mask:0xf bank_mask:0xf
	v_mov_b32_dpp v83, v23 row_ror:1 row_mask:0xf bank_mask:0xf
	v_mov_b32_dpp v75, v27 row_ror:15 row_mask:0xf bank_mask:0xf
	ds_read_b128 v[40:43], v223 offset:9744
	ds_read_b128 v[36:39], v223 offset:10768
	ds_read_b128 v[32:35], v223 offset:11792
	ds_read_b128 v[44:47], v223 offset:8720
	ds_read_b128 v[88:91], v221 offset:304
	s_and_b64 vcc, exec, s[60:61]
	v_mov_b32_e32 v85, 0
	v_mov_b32_e32 v86, 0
	v_mov_b32_e32 v87, 0
	s_cbranch_vccnz .LBB0_1187
	ds_read_b128 v[84:87], v104 offset:48
.LBB0_1187:
	s_waitcnt lgkmcnt(5)
	v_cndmask_b32_e64 v93, v99, v93, s[48:49]
	v_cndmask_b32_e64 v92, v98, v92, s[48:49]
	v_pk_mul_f32 v[92:93], v[60:61], v[92:93]
	v_cndmask_b32_e64 v83, v83, v95, s[48:49]
	v_pk_fma_f32 v[92:93], v[24:25], v[56:57], v[92:93]
	v_cndmask_b32_e64 v82, v82, v94, s[48:49]
	v_pk_fma_f32 v[92:93], v[28:29], v[48:49], v[92:93]
	v_pk_mul_f32 v[82:83], v[62:63], v[82:83]
	v_pk_add_f32 v[98:99], v[52:53], v[92:93]
	v_pk_fma_f32 v[82:83], v[26:27], v[58:59], v[82:83]
	v_mul_f32_e32 v92, 0xbfb8aa3b, v98
	v_exp_f32_e32 v92, v92
	v_mul_f32_e32 v93, 0xbfb8aa3b, v99
	v_exp_f32_e32 v93, v93
	v_pk_fma_f32 v[82:83], v[30:31], v[50:51], v[82:83]
	v_add_f32_e32 v92, 1.0, v92
	v_pk_add_f32 v[82:83], v[54:55], v[82:83]
	v_rcp_f32_e32 v100, v92
	v_add_f32_e32 v92, 1.0, v93
	v_mul_f32_e32 v93, 0xbfb8aa3b, v82
	v_exp_f32_e32 v93, v93
	v_mul_f32_e32 v94, 0xbfb8aa3b, v83
	v_rcp_f32_e32 v101, v92
	v_exp_f32_e32 v95, v94
	v_add_f32_e32 v92, 1.0, v93
	v_rcp_f32_e32 v94, v92
	v_mov_b32_dpp v93, v4 row_ror:1 row_mask:0xf bank_mask:0xf
	s_waitcnt lgkmcnt(0)
	v_cndmask_b32_e64 v102, v93, v88, s[48:49]
	v_add_f32_e32 v92, 1.0, v95
	v_mov_b32_dpp v104, v7 row_ror:1 row_mask:0xf bank_mask:0xf
	v_mov_b32_dpp v88, v5 row_ror:1 row_mask:0xf bank_mask:0xf
	v_cndmask_b32_e64 v103, v88, v89, s[48:49]
	v_rcp_f32_e32 v95, v92
	v_cndmask_b32_e64 v91, v104, v91, s[48:49]
	v_mov_b32_dpp v88, v6 row_ror:1 row_mask:0xf bank_mask:0xf
	v_cndmask_b32_e64 v90, v88, v90, s[48:49]
	v_pk_mul_f32 v[90:91], v[46:47], v[90:91]
	v_pk_mul_f32 v[102:103], v[44:45], v[102:103]
	v_pk_fma_f32 v[90:91], v[14:15], v[42:43], v[90:91]
	v_pk_fma_f32 v[102:103], v[12:13], v[40:41], v[102:103]
	v_pk_fma_f32 v[90:91], v[10:11], v[38:39], v[90:91]
	v_pk_fma_f32 v[102:103], v[8:9], v[36:37], v[102:103]
	v_pk_add_f32 v[102:103], v[32:33], v[102:103]
	v_pk_add_f32 v[90:91], v[34:35], v[90:91]
	v_pk_mul_f32 v[98:99], v[98:99], v[100:101]
	v_pk_mul_f32 v[82:83], v[82:83], v[94:95]
	v_mov_b32_dpp v92, v12 row_ror:15 row_mask:0xf bank_mask:0xf
	v_mov_b32_dpp v93, v13 row_ror:15 row_mask:0xf bank_mask:0xf
	v_mov_b32_dpp v89, v14 row_ror:15 row_mask:0xf bank_mask:0xf
	v_mov_b32_dpp v88, v15 row_ror:15 row_mask:0xf bank_mask:0xf
	v_pk_mul_f32 v[90:91], v[82:83], v[90:91]
	v_pk_mul_f32 v[82:83], v[98:99], v[102:103]
	s_nop 0
	v_cvt_pk_bf16_f32 v82, v82, v83
	v_cvt_pk_bf16_f32 v83, v90, v91
	s_and_saveexec_b64 s[22:23], s[54:55]
	s_cbranch_execz .LBB0_1189
	v_add_u32_e32 v90, 0x80, v194
	v_add_u32_e32 v94, s2, v90
	v_mov_b64_e32 v[90:91], s[88:89]
	v_mad_i64_i32 v[90:91], s[34:35], v94, s3, v[90:91]
	v_lshl_add_u64 v[90:91], v[188:189], 1, v[90:91]
	global_store_dwordx4 v[90:91], v[80:83], off
